# rwkv_finish: bonus-term loads issued with the other row loads (one memory latency per row instead of two), counted vmcnt
# speedup vs baseline: 1.0247x; 1.0037x over previous
; __device__ __forceinline__ unsigned pack2(float a, float b) { unsigned r; asm("s_nop 1\n\tv_cvt_pk_bf16_f32 %0, %1, %2" : "=v"(r) : "v"(a), "v"(b)); return r; }
; __device__ __forceinline__ float bf2f(bf16_t b) { return __uint_as_float(((unsigned)b) << 16); }
; __device__ __forceinline__ float red16(float x) { x = red8(x); x += dppf<0x140>(x); return x; }
; __device__ __forceinline__ void rwkv_finish_phase(const Params& p) {
;     ...
;   for (int row = blockIdx.x * 2 + rs; row < TALL; row += gridDim.x * 2) {
;     uint2 a = *(const uint2*)(Y0 + (size_t)row * DM + c4), bq = *(const uint2*)(Y1 + (size_t)row * DM + c4);
;     uint2 vv = *(const uint2*)(PROJ + (size_t)row * 3584 + 2048 + c4), gv = *(const uint2*)(G + (size_t)row * DM + c4);
;     float y0 = bf2f(a.x & 0xffff) + bf2f(bq.x & 0xffff), y1 = bf2f(a.x >> 16) + bf2f(bq.x >> 16);
;     float y2 = bf2f(a.y & 0xffff) + bf2f(bq.y & 0xffff), y3 = bf2f(a.y >> 16) + bf2f(bq.y >> 16);
;     float mean = red16(y0 + y1 + y2 + y3) * (1.f / 64.f);
;     float d0 = y0 - mean, d1 = y1 - mean, d2 = y2 - mean, d3 = y3 - mean;
;     float var = red16(d0 * d0 + d1 * d1 + d2 * d2 + d3 * d3) * (1.f / 64.f);
;     float rstd = rsqrtf(var + 64e-5f);
;     float bon = BON[(size_t)row * 16 + hd] + BON[((size_t)TALL + row) * 16 + hd];
;     float o0 = (d0 * rstd * lg.x + lb.x + bon * bf2f(vv.x & 0xffff)) * bf2f(gv.x & 0xffff);
;     float o1 = (d1 * rstd * lg.y + lb.y + bon * bf2f(vv.x >> 16)) * bf2f(gv.x >> 16);
;     float o2 = (d2 * rstd * lg.z + lb.z + bon * bf2f(vv.y & 0xffff)) * bf2f(gv.y & 0xffff);
;     float o3 = (d3 * rstd * lg.w + lb.w + bon * bf2f(vv.y >> 16)) * bf2f(gv.y >> 16);
;     uint2 pk; pk.x = pack2(o0, o1); pk.y = pack2(o2, o3);
;     *(uint2*)(Y0 + (size_t)row * DM + c4) = pk;
;   }
.LBB0_92:
	v_ashrrev_i32_e32 v9, 31, v8
	v_lshlrev_b64 v[18:19], 11, v[8:9]
	s_waitcnt vmcnt(5)
	v_lshl_add_u64 v[20:21], v[10:11], 0, v[18:19]
	s_waitcnt vmcnt(3)
	v_lshl_add_u64 v[24:25], v[12:13], 0, v[18:19]
	s_waitcnt lgkmcnt(0)
	global_load_dwordx2 v[22:23], v[20:21], off
	v_mov_b64_e32 v[26:27], s[54:55]
	global_load_dwordx2 v[24:25], v[24:25], off
	s_movk_i32 s2, 0x1c00
	v_mad_i64_i32 v[26:27], s[26:27], v8, s2, v[26:27]
	v_lshl_add_u64 v[26:27], v[26:27], 0, v[160:161]
	s_mov_b32 s2, 0x18039000
	v_add_co_u32_e32 v26, vcc, s2, v26
	v_lshl_add_u64 v[18:19], v[14:15], 0, v[18:19]
	s_nop 0
	v_addc_co_u32_e32 v27, vcc, 0, v27, vcc
	global_load_dwordx2 v[26:27], v[26:27], off offset:256
	s_mov_b32 s2, 0x420000
	global_load_dwordx2 v[18:19], v[18:19], off
	v_lshlrev_b64 v[36:37], 6, v[8:9]
	v_lshl_add_u64 v[36:37], s[82:83], 0, v[36:37]
	v_mov_b32_e32 v17, v161
	v_lshl_add_u64 v[36:37], v[36:37], 0, v[16:17]
	global_load_dword v40, v[36:37], off
	v_add_co_u32_e32 v38, vcc, s2, v36
	s_nop 1
	v_addc_co_u32_e32 v39, vcc, 0, v37, vcc
	global_load_dword v41, v[38:39], off
	s_waitcnt vmcnt(5)
	v_lshlrev_b32_e32 v28, 16, v22
	v_and_b32_e32 v29, 0xffff0000, v22
	s_waitcnt vmcnt(4)
	v_lshlrev_b32_e32 v30, 16, v24
	v_and_b32_e32 v31, 0xffff0000, v24
	v_lshlrev_b32_e32 v33, 16, v23
	v_lshlrev_b32_e32 v35, 16, v25
	v_and_b32_e32 v32, 0xffff0000, v23
	v_and_b32_e32 v34, 0xffff0000, v25
	v_pk_add_f32 v[24:25], v[28:29], v[30:31]
	v_pk_add_f32 v[22:23], v[32:33], v[34:35]
	v_add_f32_e32 v17, v24, v25
	v_add_f32_e32 v17, v17, v23
	v_add_f32_e32 v17, v22, v17
	s_nop 1
	v_add_f32_dpp v17, v17, v17 quad_perm:[1,0,3,2] row_mask:0xf bank_mask:0xf bound_ctrl:1
	s_nop 1
	v_add_f32_dpp v17, v17, v17 quad_perm:[2,3,0,1] row_mask:0xf bank_mask:0xf bound_ctrl:1
	s_nop 1
	v_add_f32_dpp v17, v17, v17 row_half_mirror row_mask:0xf bank_mask:0xf bound_ctrl:1
	s_nop 1
	v_add_f32_dpp v17, v17, v17 row_mirror row_mask:0xf bank_mask:0xf bound_ctrl:1
	v_mul_f32_e32 v28, 0x3c800000, v17
	v_pk_add_f32 v[24:25], v[24:25], v[28:29] op_sel_hi:[1,0] neg_lo:[0,1] neg_hi:[0,1]
	v_pk_add_f32 v[22:23], v[22:23], v[28:29] op_sel_hi:[1,0] neg_lo:[0,1] neg_hi:[0,1]
	v_pk_mul_f32 v[28:29], v[24:25], v[24:25]
	v_pk_mul_f32 v[30:31], v[22:23], v[22:23]
	v_add_f32_e32 v17, v28, v29
	v_add_f32_e32 v17, v31, v17
	v_add_f32_e32 v17, v30, v17
	s_nop 1
	v_add_f32_dpp v17, v17, v17 quad_perm:[1,0,3,2] row_mask:0xf bank_mask:0xf bound_ctrl:1
	s_nop 1
	v_add_f32_dpp v17, v17, v17 quad_perm:[2,3,0,1] row_mask:0xf bank_mask:0xf bound_ctrl:1
	s_nop 1
	v_add_f32_dpp v17, v17, v17 row_half_mirror row_mask:0xf bank_mask:0xf bound_ctrl:1
	s_nop 1
	v_add_f32_dpp v17, v17, v17 row_mirror row_mask:0xf bank_mask:0xf bound_ctrl:1
	v_fmamk_f32 v17, v17, 0x3c800000, v186
	v_cmp_gt_f32_e32 vcc, s7, v17
	v_mul_f32_e32 v28, 0x4b800000, v17
	s_nop 0
	v_cndmask_b32_e32 v17, v17, v28, vcc
	v_rsq_f32_e32 v17, v17
	s_nop 0
	v_mul_f32_e32 v28, 0x45800000, v17
	v_cndmask_b32_e32 v30, v17, v28, vcc
	v_mul_f32_e32 v23, v23, v30
	v_fma_f32 v23, v2, v23, v6
	v_mul_f32_e32 v22, v22, v30
	v_add_u32_e32 v8, s29, v8
	v_fma_f32 v22, v3, v22, v7
	v_cmp_lt_i32_e32 vcc, s25, v8
	s_or_b64 s[4:5], vcc, s[4:5]
	s_waitcnt vmcnt(0)
	v_add_f32_e32 v9, v40, v41
	v_mul_f32_e32 v17, v24, v30
	v_fma_f32 v17, v0, v17, v4
	v_lshlrev_b32_e32 v24, 16, v26
	v_fmac_f32_e32 v17, v9, v24
	v_lshlrev_b32_e32 v24, 16, v18
	v_mul_f32_e32 v17, v17, v24
	v_mul_f32_e32 v24, v25, v30
	v_fma_f32 v24, v1, v24, v5
	v_and_b32_e32 v25, 0xffff0000, v26
	v_fmac_f32_e32 v24, v9, v25
	v_and_b32_e32 v18, 0xffff0000, v18
	v_mul_f32_e32 v18, v24, v18
	v_lshlrev_b32_e32 v24, 16, v27
	v_fmac_f32_e32 v23, v9, v24
	v_lshlrev_b32_e32 v24, 16, v19
	v_mul_f32_e32 v23, v23, v24
	v_and_b32_e32 v24, 0xffff0000, v27
	v_fmac_f32_e32 v22, v9, v24
	v_and_b32_e32 v9, 0xffff0000, v19
	v_mul_f32_e32 v9, v22, v9
	s_nop 1
	v_cvt_pk_bf16_f32 v18, v17, v18
	s_nop 1
	v_cvt_pk_bf16_f32 v19, v23, v9
	global_store_dwordx2 v[20:21], v[18:19], off
	s_andn2_b64 exec, exec, s[4:5]
	s_cbranch_execnz .LBB0_92
